# first rms-norm phase rows hand-written too (fp32 in): four rows of a wave requested together
# baseline (speedup 1.0000x reference)
.Lnorm0_rows_done:
	s_barrier
	s_load_dword s10, s[24:25], 0x0
	s_waitcnt lgkmcnt(0)
	s_add_i32 s46, s10, s46
	s_cmpk_lt_i32 s46, 0x200
	s_cbranch_scc0 .LBB0_179

.LBB0_148:
	s_or_b64 exec, exec, s[10:11]
	s_cmp_lt_i32 s47, 0x2000
	s_cselect_b32 s10, s16, s18
	s_cselect_b32 s11, s17, s19
	s_and_b32 s26, s47, 0x1fff
	v_and_b32_e32 v152, 63, v0
	v_lshlrev_b32_e32 v153, 5, v152
	v_add_u32_e32 v28, s26, v1
	v_lshl_add_u32 v28, v28, 12, v153
	v_add_u32_e32 v29, 0x1000, v28
	v_add_u32_e32 v30, 0x2000, v28
	v_add_u32_e32 v31, 0x3000, v28
	global_load_dwordx4 v[84:87], v28, s[10:11]
	global_load_dwordx4 v[88:91], v28, s[10:11] offset:16
	global_load_dwordx4 v[92:95], v28, s[10:11] offset:2048
	global_load_dwordx4 v[96:99], v28, s[10:11] offset:2064
	global_load_dwordx4 v[100:103], v29, s[10:11]
	global_load_dwordx4 v[104:107], v29, s[10:11] offset:16
	global_load_dwordx4 v[108:111], v29, s[10:11] offset:2048
	global_load_dwordx4 v[112:115], v29, s[10:11] offset:2064
	global_load_dwordx4 v[116:119], v30, s[10:11]
	global_load_dwordx4 v[120:123], v30, s[10:11] offset:16
	global_load_dwordx4 v[124:127], v30, s[10:11] offset:2048
	global_load_dwordx4 v[128:131], v30, s[10:11] offset:2064
	global_load_dwordx4 v[132:135], v31, s[10:11]
	global_load_dwordx4 v[136:139], v31, s[10:11] offset:16
	global_load_dwordx4 v[140:143], v31, s[10:11] offset:2048
	global_load_dwordx4 v[144:147], v31, s[10:11] offset:2064
	s_waitcnt lgkmcnt(0)
	s_barrier
	ds_read_b128 v[46:49], v153 offset:4096
	ds_read_b128 v[50:53], v153 offset:4112
	ds_read_b128 v[54:57], v153 offset:6144
	ds_read_b128 v[58:61], v153 offset:6160
	ds_read_b128 v[2:5], v153
	ds_read_b128 v[6:9], v153 offset:16
	ds_read_b128 v[10:13], v153 offset:2048
	ds_read_b128 v[14:17], v153 offset:2064
	s_waitcnt vmcnt(12)
	v_mul_f32_e32 v148, v84, v84
	v_mul_f32_e32 v28, v85, v85
	v_fmac_f32_e32 v148, v86, v86
	v_fmac_f32_e32 v28, v87, v87
	v_fmac_f32_e32 v148, v88, v88
	v_fmac_f32_e32 v28, v89, v89
	v_fmac_f32_e32 v148, v90, v90
	v_fmac_f32_e32 v28, v91, v91
	v_fmac_f32_e32 v148, v92, v92
	v_fmac_f32_e32 v28, v93, v93
	v_fmac_f32_e32 v148, v94, v94
	v_fmac_f32_e32 v28, v95, v95
	v_fmac_f32_e32 v148, v96, v96
	v_fmac_f32_e32 v28, v97, v97
	v_fmac_f32_e32 v148, v98, v98
	v_fmac_f32_e32 v28, v99, v99
	v_add_f32_e32 v148, v148, v28
	s_waitcnt vmcnt(8)
	v_mul_f32_e32 v149, v100, v100
	v_mul_f32_e32 v29, v101, v101
	v_fmac_f32_e32 v149, v102, v102
	v_fmac_f32_e32 v29, v103, v103
	v_fmac_f32_e32 v149, v104, v104
	v_fmac_f32_e32 v29, v105, v105
	v_fmac_f32_e32 v149, v106, v106
	v_fmac_f32_e32 v29, v107, v107
	v_fmac_f32_e32 v149, v108, v108
	v_fmac_f32_e32 v29, v109, v109
	v_fmac_f32_e32 v149, v110, v110
	v_fmac_f32_e32 v29, v111, v111
	v_fmac_f32_e32 v149, v112, v112
	v_fmac_f32_e32 v29, v113, v113
	v_fmac_f32_e32 v149, v114, v114
	v_fmac_f32_e32 v29, v115, v115
	v_add_f32_e32 v149, v149, v29
	s_waitcnt vmcnt(4)
	v_mul_f32_e32 v150, v116, v116
	v_mul_f32_e32 v30, v117, v117
	v_fmac_f32_e32 v150, v118, v118
	v_fmac_f32_e32 v30, v119, v119
	v_fmac_f32_e32 v150, v120, v120
	v_fmac_f32_e32 v30, v121, v121
	v_fmac_f32_e32 v150, v122, v122
	v_fmac_f32_e32 v30, v123, v123
	v_fmac_f32_e32 v150, v124, v124
	v_fmac_f32_e32 v30, v125, v125
	v_fmac_f32_e32 v150, v126, v126
	v_fmac_f32_e32 v30, v127, v127
	v_fmac_f32_e32 v150, v128, v128
	v_fmac_f32_e32 v30, v129, v129
	v_fmac_f32_e32 v150, v130, v130
	v_fmac_f32_e32 v30, v131, v131
	v_add_f32_e32 v150, v150, v30
	s_waitcnt vmcnt(0)
	v_mul_f32_e32 v151, v132, v132
	v_mul_f32_e32 v31, v133, v133
	v_fmac_f32_e32 v151, v134, v134
	v_fmac_f32_e32 v31, v135, v135
	v_fmac_f32_e32 v151, v136, v136
	v_fmac_f32_e32 v31, v137, v137
	v_fmac_f32_e32 v151, v138, v138
	v_fmac_f32_e32 v31, v139, v139
	v_fmac_f32_e32 v151, v140, v140
	v_fmac_f32_e32 v31, v141, v141
	v_fmac_f32_e32 v151, v142, v142
	v_fmac_f32_e32 v31, v143, v143
	v_fmac_f32_e32 v151, v144, v144
	v_fmac_f32_e32 v31, v145, v145
	v_fmac_f32_e32 v151, v146, v146
	v_fmac_f32_e32 v31, v147, v147
	v_add_f32_e32 v151, v151, v31
	ds_bpermute_b32 v28, v36, v148
	ds_bpermute_b32 v29, v36, v149
	ds_bpermute_b32 v30, v36, v150
	ds_bpermute_b32 v31, v36, v151
	s_waitcnt lgkmcnt(3)
	v_add_f32_e32 v148, v148, v28
	s_waitcnt lgkmcnt(2)
	v_add_f32_e32 v149, v149, v29
	s_waitcnt lgkmcnt(1)
	v_add_f32_e32 v150, v150, v30
	s_waitcnt lgkmcnt(0)
	v_add_f32_e32 v151, v151, v31
	ds_bpermute_b32 v28, v37, v148
	ds_bpermute_b32 v29, v37, v149
	ds_bpermute_b32 v30, v37, v150
	ds_bpermute_b32 v31, v37, v151
	s_waitcnt lgkmcnt(3)
	v_add_f32_e32 v148, v148, v28
	s_waitcnt lgkmcnt(2)
	v_add_f32_e32 v149, v149, v29
	s_waitcnt lgkmcnt(1)
	v_add_f32_e32 v150, v150, v30
	s_waitcnt lgkmcnt(0)
	v_add_f32_e32 v151, v151, v31
	ds_bpermute_b32 v28, v38, v148
	ds_bpermute_b32 v29, v38, v149
	ds_bpermute_b32 v30, v38, v150
	ds_bpermute_b32 v31, v38, v151
	s_waitcnt lgkmcnt(3)
	v_add_f32_e32 v148, v148, v28
	s_waitcnt lgkmcnt(2)
	v_add_f32_e32 v149, v149, v29
	s_waitcnt lgkmcnt(1)
	v_add_f32_e32 v150, v150, v30
	s_waitcnt lgkmcnt(0)
	v_add_f32_e32 v151, v151, v31
	ds_bpermute_b32 v28, v39, v148
	ds_bpermute_b32 v29, v39, v149
	ds_bpermute_b32 v30, v39, v150
	ds_bpermute_b32 v31, v39, v151
	s_waitcnt lgkmcnt(3)
	v_add_f32_e32 v148, v148, v28
	s_waitcnt lgkmcnt(2)
	v_add_f32_e32 v149, v149, v29
	s_waitcnt lgkmcnt(1)
	v_add_f32_e32 v150, v150, v30
	s_waitcnt lgkmcnt(0)
	v_add_f32_e32 v151, v151, v31
	ds_bpermute_b32 v28, v40, v148
	ds_bpermute_b32 v29, v40, v149
	ds_bpermute_b32 v30, v40, v150
	ds_bpermute_b32 v31, v40, v151
	s_waitcnt lgkmcnt(3)
	v_add_f32_e32 v148, v148, v28
	s_waitcnt lgkmcnt(2)
	v_add_f32_e32 v149, v149, v29
	s_waitcnt lgkmcnt(1)
	v_add_f32_e32 v150, v150, v30
	s_waitcnt lgkmcnt(0)
	v_add_f32_e32 v151, v151, v31
	ds_bpermute_b32 v28, v41, v148
	ds_bpermute_b32 v29, v41, v149
	ds_bpermute_b32 v30, v41, v150
	ds_bpermute_b32 v31, v41, v151
	s_waitcnt lgkmcnt(3)
	v_add_f32_e32 v148, v148, v28
	s_waitcnt lgkmcnt(2)
	v_add_f32_e32 v149, v149, v29
	s_waitcnt lgkmcnt(1)
	v_add_f32_e32 v150, v150, v30
	s_waitcnt lgkmcnt(0)
	v_add_f32_e32 v151, v151, v31
	v_fmamk_f32 v148, v148, 0x3a800000, v45
	v_fmamk_f32 v149, v149, 0x3a800000, v45
	v_fmamk_f32 v150, v150, 0x3a800000, v45
	v_fmamk_f32 v151, v151, 0x3a800000, v45
	v_rsq_f32_e32 v148, v148
	v_rsq_f32_e32 v149, v149
	v_rsq_f32_e32 v150, v150
	v_rsq_f32_e32 v151, v151
	v_lshlrev_b32_e32 v28, 3, v152
	v_add_u32_e32 v29, s47, v1
	v_lshl_add_u32 v28, v29, 11, v28
	v_mov_b32_e32 v29, 0
	v_lshl_add_u64 v[30:31], v[28:29], 0, v[26:27]
	v_add_u32_e32 v28, 0x1000, v28
	v_lshl_add_u64 v[32:33], v[28:29], 0, v[26:27]
	v_mul_f32_e32 v152, v148, v84
	v_mul_f32_e32 v153, v148, v85
	v_fma_f32 v152, v46, v152, v2
	v_fma_f32 v153, v47, v153, v3
	v_cvt_pk_bf16_f32 v84, v152, v153
	v_mul_f32_e32 v152, v148, v86
	v_mul_f32_e32 v153, v148, v87
	v_fma_f32 v152, v48, v152, v4
	v_fma_f32 v153, v49, v153, v5
	v_cvt_pk_bf16_f32 v85, v152, v153
	v_mul_f32_e32 v152, v148, v88
	v_mul_f32_e32 v153, v148, v89
	v_fma_f32 v152, v50, v152, v6
	v_fma_f32 v153, v51, v153, v7
	v_cvt_pk_bf16_f32 v86, v152, v153
	v_mul_f32_e32 v152, v148, v90
	v_mul_f32_e32 v153, v148, v91
	v_fma_f32 v152, v52, v152, v8
	v_fma_f32 v153, v53, v153, v9
	v_cvt_pk_bf16_f32 v87, v152, v153
	global_store_dwordx4 v[30:31], v[84:87], off
	v_mul_f32_e32 v152, v148, v92
	v_mul_f32_e32 v153, v148, v93
	v_fma_f32 v152, v54, v152, v10
	v_fma_f32 v153, v55, v153, v11
	v_cvt_pk_bf16_f32 v92, v152, v153
	v_mul_f32_e32 v152, v148, v94
	v_mul_f32_e32 v153, v148, v95
	v_fma_f32 v152, v56, v152, v12
	v_fma_f32 v153, v57, v153, v13
	v_cvt_pk_bf16_f32 v93, v152, v153
	v_mul_f32_e32 v152, v148, v96
	v_mul_f32_e32 v153, v148, v97
	v_fma_f32 v152, v58, v152, v14
	v_fma_f32 v153, v59, v153, v15
	v_cvt_pk_bf16_f32 v94, v152, v153
	v_mul_f32_e32 v152, v148, v98
	v_mul_f32_e32 v153, v148, v99
	v_fma_f32 v152, v60, v152, v16
	v_fma_f32 v153, v61, v153, v17
	v_cvt_pk_bf16_f32 v95, v152, v153
	global_store_dwordx4 v[30:31], v[92:95], off offset:1024
	v_mul_f32_e32 v152, v149, v100
	v_mul_f32_e32 v153, v149, v101
	v_fma_f32 v152, v46, v152, v2
	v_fma_f32 v153, v47, v153, v3
	v_cvt_pk_bf16_f32 v100, v152, v153
	v_mul_f32_e32 v152, v149, v102
	v_mul_f32_e32 v153, v149, v103
	v_fma_f32 v152, v48, v152, v4
	v_fma_f32 v153, v49, v153, v5
	v_cvt_pk_bf16_f32 v101, v152, v153
	v_mul_f32_e32 v152, v149, v104
	v_mul_f32_e32 v153, v149, v105
	v_fma_f32 v152, v50, v152, v6
	v_fma_f32 v153, v51, v153, v7
	v_cvt_pk_bf16_f32 v102, v152, v153
	v_mul_f32_e32 v152, v149, v106
	v_mul_f32_e32 v153, v149, v107
	v_fma_f32 v152, v52, v152, v8
	v_fma_f32 v153, v53, v153, v9
	v_cvt_pk_bf16_f32 v103, v152, v153
	global_store_dwordx4 v[30:31], v[100:103], off offset:2048
	v_mul_f32_e32 v152, v149, v108
	v_mul_f32_e32 v153, v149, v109
	v_fma_f32 v152, v54, v152, v10
	v_fma_f32 v153, v55, v153, v11
	v_cvt_pk_bf16_f32 v108, v152, v153
	v_mul_f32_e32 v152, v149, v110
	v_mul_f32_e32 v153, v149, v111
	v_fma_f32 v152, v56, v152, v12
	v_fma_f32 v153, v57, v153, v13
	v_cvt_pk_bf16_f32 v109, v152, v153
	v_mul_f32_e32 v152, v149, v112
	v_mul_f32_e32 v153, v149, v113
	v_fma_f32 v152, v58, v152, v14
	v_fma_f32 v153, v59, v153, v15
	v_cvt_pk_bf16_f32 v110, v152, v153
	v_mul_f32_e32 v152, v149, v114
	v_mul_f32_e32 v153, v149, v115
	v_fma_f32 v152, v60, v152, v16
	v_fma_f32 v153, v61, v153, v17
	v_cvt_pk_bf16_f32 v111, v152, v153
	global_store_dwordx4 v[30:31], v[108:111], off offset:3072
	v_mul_f32_e32 v152, v150, v116
	v_mul_f32_e32 v153, v150, v117
	v_fma_f32 v152, v46, v152, v2
	v_fma_f32 v153, v47, v153, v3
	v_cvt_pk_bf16_f32 v116, v152, v153
	v_mul_f32_e32 v152, v150, v118
	v_mul_f32_e32 v153, v150, v119
	v_fma_f32 v152, v48, v152, v4
	v_fma_f32 v153, v49, v153, v5
	v_cvt_pk_bf16_f32 v117, v152, v153
	v_mul_f32_e32 v152, v150, v120
	v_mul_f32_e32 v153, v150, v121
	v_fma_f32 v152, v50, v152, v6
	v_fma_f32 v153, v51, v153, v7
	v_cvt_pk_bf16_f32 v118, v152, v153
	v_mul_f32_e32 v152, v150, v122
	v_mul_f32_e32 v153, v150, v123
	v_fma_f32 v152, v52, v152, v8
	v_fma_f32 v153, v53, v153, v9
	v_cvt_pk_bf16_f32 v119, v152, v153
	global_store_dwordx4 v[32:33], v[116:119], off
	v_mul_f32_e32 v152, v150, v124
	v_mul_f32_e32 v153, v150, v125
	v_fma_f32 v152, v54, v152, v10
	v_fma_f32 v153, v55, v153, v11
	v_cvt_pk_bf16_f32 v124, v152, v153
	v_mul_f32_e32 v152, v150, v126
	v_mul_f32_e32 v153, v150, v127
	v_fma_f32 v152, v56, v152, v12
	v_fma_f32 v153, v57, v153, v13
	v_cvt_pk_bf16_f32 v125, v152, v153
	v_mul_f32_e32 v152, v150, v128
	v_mul_f32_e32 v153, v150, v129
	v_fma_f32 v152, v58, v152, v14
	v_fma_f32 v153, v59, v153, v15
	v_cvt_pk_bf16_f32 v126, v152, v153
	v_mul_f32_e32 v152, v150, v130
	v_mul_f32_e32 v153, v150, v131
	v_fma_f32 v152, v60, v152, v16
	v_fma_f32 v153, v61, v153, v17
	v_cvt_pk_bf16_f32 v127, v152, v153
	global_store_dwordx4 v[32:33], v[124:127], off offset:1024
	v_mul_f32_e32 v152, v151, v132
	v_mul_f32_e32 v153, v151, v133
	v_fma_f32 v152, v46, v152, v2
	v_fma_f32 v153, v47, v153, v3
	v_cvt_pk_bf16_f32 v132, v152, v153
	v_mul_f32_e32 v152, v151, v134
	v_mul_f32_e32 v153, v151, v135
	v_fma_f32 v152, v48, v152, v4
	v_fma_f32 v153, v49, v153, v5
	v_cvt_pk_bf16_f32 v133, v152, v153
	v_mul_f32_e32 v152, v151, v136
	v_mul_f32_e32 v153, v151, v137
	v_fma_f32 v152, v50, v152, v6
	v_fma_f32 v153, v51, v153, v7
	v_cvt_pk_bf16_f32 v134, v152, v153
	v_mul_f32_e32 v152, v151, v138
	v_mul_f32_e32 v153, v151, v139
	v_fma_f32 v152, v52, v152, v8
	v_fma_f32 v153, v53, v153, v9
	v_cvt_pk_bf16_f32 v135, v152, v153
	global_store_dwordx4 v[32:33], v[132:135], off offset:2048
	v_mul_f32_e32 v152, v151, v140
	v_mul_f32_e32 v153, v151, v141
	v_fma_f32 v152, v54, v152, v10
	v_fma_f32 v153, v55, v153, v11
	v_cvt_pk_bf16_f32 v140, v152, v153
	v_mul_f32_e32 v152, v151, v142
	v_mul_f32_e32 v153, v151, v143
	v_fma_f32 v152, v56, v152, v12
	v_fma_f32 v153, v57, v153, v13
	v_cvt_pk_bf16_f32 v141, v152, v153
	v_mul_f32_e32 v152, v151, v144
	v_mul_f32_e32 v153, v151, v145
	v_fma_f32 v152, v58, v152, v14
	v_fma_f32 v153, v59, v153, v15
	v_cvt_pk_bf16_f32 v142, v152, v153
	v_mul_f32_e32 v152, v151, v146
	v_mul_f32_e32 v153, v151, v147
	v_fma_f32 v152, v60, v152, v16
	v_fma_f32 v153, v61, v153, v17
	v_cvt_pk_bf16_f32 v143, v152, v153
	global_store_dwordx4 v[32:33], v[140:143], off offset:3072
	s_branch .Lnorm0_rows_done
